# static priority variant: waves 0-3 raised instead of 4-7, flips still removed
# speedup vs baseline: 1.0133x; 1.0008x over previous
_Z14fwd_megakernel6Params:
	s_load_dwordx2 s[96:97], s[0:1], 0x128
	s_load_dword s52, s[0:1], 0x130
	s_add_u32 s54, s0, 0x128
	s_addc_u32 s55, s1, 0
	v_and_b32_e32 v171, 0x3ff, v0
	v_cmp_eq_u32_e64 s[6:7], 0, v171
	v_readfirstlane_b32 s3, v171
	s_nop 3
	s_lshr_b32 s3, s3, 6
	s_cmp_lt_u32 s3, 4
	s_cbranch_scc0 .Lprio_skip
	s_setprio 1
